# GEMM tile loops (6 of 8 instances): accumulators zeroed with 64 v_mov_b64 instead of 128 v_mov_b32
# speedup vs baseline: 1.0102x; 1.0037x over previous
;     __device__ bool next(int i, Unit& u) const { if (!so.next(i, u)) return false; u.ks = u.pn >= 16 ? 1 : 0; return true; }
; template <class Epi, class Order>
; __device__ __forceinline__ void gemm_phase(LAS unsigned char* lds, const Gemm g, const Order& S, const Epi& E) {
;     ...
;         const bool has_next = S.next(ui + 1, nxt);
;         const char* nA = has_next ? (const char*)g.A + (size_t)nxt.pm * tstep + (size_t)nxt.ks * sstep : cA; const char* nB = has_next ? (const char*)g.Bt + (size_t)nxt.pn * tstep + (size_t)nxt.ks * sstep : cB;
;     ...
; #pragma unroll
;         for (int a = 0; a < 2; ++a)
; #pragma unroll
;             for (int b = 0; b < 2; ++b)
; #pragma unroll
;                 for (int m = 0; m < 4; ++m)
; #pragma unroll
;                     for (int n = 0; n < 2; ++n) acc[a][b][m][n] = (f32x4){0.f, 0.f, 0.f, 0.f};
;         cur = nxt; cA = nA; cB = nB; ++ui;
.LBB0_221:
	s_ashr_i32 s11, s10, 31
	v_cmp_lt_i64_e32 vcc, s[16:17], v[140:141]
	s_lshl_b64 s[16:17], s[10:11], 20
	s_add_u32 s16, s64, s16
	s_addc_u32 s17, s65, s17
	s_and_b64 s[20:21], vcc, exec
	s_cselect_b32 s11, s17, s39
	s_cselect_b32 s73, s16, s38
	s_ashr_i32 s9, s8, 31
	s_lshl_b64 s[20:21], s[8:9], 20
	s_add_u32 s20, s35, s20
	s_addc_u32 s21, s46, s21
	s_and_b64 s[24:25], vcc, exec
	s_cselect_b32 s9, s21, s43
	s_cselect_b32 s84, s20, s42
	s_add_u32 s38, s38, 0x80080
	s_addc_u32 s39, s39, 0
	s_add_u32 s85, s42, 0x100
	v_mov_b64_e32 v[0:1], 0
	v_mov_b64_e32 v[2:3], 0
	v_mov_b64_e32 v[4:5], 0
	v_mov_b64_e32 v[6:7], 0
	v_mov_b64_e32 v[8:9], 0
	v_mov_b64_e32 v[10:11], 0
	v_mov_b64_e32 v[12:13], 0
	v_mov_b64_e32 v[14:15], 0
	v_mov_b64_e32 v[16:17], 0
	v_mov_b64_e32 v[18:19], 0
	v_mov_b64_e32 v[20:21], 0
	v_mov_b64_e32 v[22:23], 0
	v_mov_b64_e32 v[24:25], 0
	v_mov_b64_e32 v[26:27], 0
	v_mov_b64_e32 v[28:29], 0
	v_mov_b64_e32 v[30:31], 0
	v_mov_b64_e32 v[32:33], 0
	v_mov_b64_e32 v[34:35], 0
	v_mov_b64_e32 v[36:37], 0
	v_mov_b64_e32 v[38:39], 0
	v_mov_b64_e32 v[40:41], 0
	v_mov_b64_e32 v[42:43], 0
	v_mov_b64_e32 v[44:45], 0
	v_mov_b64_e32 v[46:47], 0
	v_mov_b64_e32 v[48:49], 0
	v_mov_b64_e32 v[50:51], 0
	v_mov_b64_e32 v[52:53], 0
	v_mov_b64_e32 v[54:55], 0
	v_mov_b64_e32 v[56:57], 0
	v_mov_b64_e32 v[58:59], 0
	v_mov_b64_e32 v[60:61], 0
	v_mov_b64_e32 v[62:63], 0
	v_mov_b64_e32 v[64:65], 0
	v_mov_b64_e32 v[66:67], 0
	v_mov_b64_e32 v[68:69], 0
	v_mov_b64_e32 v[70:71], 0
	v_mov_b64_e32 v[72:73], 0
	v_mov_b64_e32 v[74:75], 0
	v_mov_b64_e32 v[76:77], 0
	v_mov_b64_e32 v[78:79], 0
	v_mov_b64_e32 v[80:81], 0
	v_mov_b64_e32 v[82:83], 0
	v_mov_b64_e32 v[84:85], 0
	v_mov_b64_e32 v[86:87], 0
	v_mov_b64_e32 v[88:89], 0
	v_mov_b64_e32 v[90:91], 0
	v_mov_b64_e32 v[92:93], 0
	v_mov_b64_e32 v[94:95], 0
	v_mov_b64_e32 v[96:97], 0
	v_mov_b64_e32 v[98:99], 0
	v_mov_b64_e32 v[100:101], 0
	v_mov_b64_e32 v[102:103], 0
	v_mov_b64_e32 v[104:105], 0
	v_mov_b64_e32 v[106:107], 0
	v_mov_b64_e32 v[108:109], 0
	v_mov_b64_e32 v[110:111], 0
	v_mov_b64_e32 v[112:113], 0
	v_mov_b64_e32 v[114:115], 0
	v_mov_b64_e32 v[116:117], 0
	v_mov_b64_e32 v[118:119], 0
	v_mov_b64_e32 v[120:121], 0
	v_mov_b64_e32 v[122:123], 0
	v_mov_b64_e32 v[124:125], 0
	v_mov_b64_e32 v[126:127], 0
	s_addc_u32 s94, s43, 0
	s_mov_b32 s95, -2

;     __device__ bool next(int i, Unit& u) const { if (!so.next(i, u)) return false; u.ks = u.pn >= 16 ? 1 : 0; return true; }
; template <class Epi, class Order>
; __device__ __forceinline__ void gemm_phase(LAS unsigned char* lds, const Gemm g, const Order& S, const Epi& E) {
;     ...
;         const bool has_next = S.next(ui + 1, nxt);
;         const char* nA = has_next ? (const char*)g.A + (size_t)nxt.pm * tstep + (size_t)nxt.ks * sstep : cA; const char* nB = has_next ? (const char*)g.Bt + (size_t)nxt.pn * tstep + (size_t)nxt.ks * sstep : cB;
;     ...
; #pragma unroll
;         for (int a = 0; a < 2; ++a)
; #pragma unroll
;             for (int b = 0; b < 2; ++b)
; #pragma unroll
;                 for (int m = 0; m < 4; ++m)
; #pragma unroll
;                     for (int n = 0; n < 2; ++n) acc[a][b][m][n] = (f32x4){0.f, 0.f, 0.f, 0.f};
;         cur = nxt; cA = nA; cB = nB; ++ui;
.LBB0_298:
	s_add_u32 s22, s22, 0x160080
	s_addc_u32 s23, s23, 0
	s_add_u32 s46, s42, 0x100
	v_mov_b64_e32 v[0:1], 0
	v_mov_b64_e32 v[2:3], 0
	v_mov_b64_e32 v[4:5], 0
	v_mov_b64_e32 v[6:7], 0
	v_mov_b64_e32 v[8:9], 0
	v_mov_b64_e32 v[10:11], 0
	v_mov_b64_e32 v[12:13], 0
	v_mov_b64_e32 v[14:15], 0
	v_mov_b64_e32 v[16:17], 0
	v_mov_b64_e32 v[18:19], 0
	v_mov_b64_e32 v[20:21], 0
	v_mov_b64_e32 v[22:23], 0
	v_mov_b64_e32 v[24:25], 0
	v_mov_b64_e32 v[26:27], 0
	v_mov_b64_e32 v[28:29], 0
	v_mov_b64_e32 v[30:31], 0
	v_mov_b64_e32 v[32:33], 0
	v_mov_b64_e32 v[34:35], 0
	v_mov_b64_e32 v[36:37], 0
	v_mov_b64_e32 v[38:39], 0
	v_mov_b64_e32 v[40:41], 0
	v_mov_b64_e32 v[42:43], 0
	v_mov_b64_e32 v[44:45], 0
	v_mov_b64_e32 v[46:47], 0
	v_mov_b64_e32 v[48:49], 0
	v_mov_b64_e32 v[50:51], 0
	v_mov_b64_e32 v[52:53], 0
	v_mov_b64_e32 v[54:55], 0
	v_mov_b64_e32 v[56:57], 0
	v_mov_b64_e32 v[58:59], 0
	v_mov_b64_e32 v[60:61], 0
	v_mov_b64_e32 v[62:63], 0
	v_mov_b64_e32 v[64:65], 0
	v_mov_b64_e32 v[66:67], 0
	v_mov_b64_e32 v[68:69], 0
	v_mov_b64_e32 v[70:71], 0
	v_mov_b64_e32 v[72:73], 0
	v_mov_b64_e32 v[74:75], 0
	v_mov_b64_e32 v[76:77], 0
	v_mov_b64_e32 v[78:79], 0
	v_mov_b64_e32 v[80:81], 0
	v_mov_b64_e32 v[82:83], 0
	v_mov_b64_e32 v[84:85], 0
	v_mov_b64_e32 v[86:87], 0
	v_mov_b64_e32 v[88:89], 0
	v_mov_b64_e32 v[90:91], 0
	v_mov_b64_e32 v[92:93], 0
	v_mov_b64_e32 v[94:95], 0
	v_mov_b64_e32 v[96:97], 0
	v_mov_b64_e32 v[98:99], 0
	v_mov_b64_e32 v[100:101], 0
	v_mov_b64_e32 v[102:103], 0
	v_mov_b64_e32 v[104:105], 0
	v_mov_b64_e32 v[106:107], 0
	v_mov_b64_e32 v[108:109], 0
	v_mov_b64_e32 v[110:111], 0
	v_mov_b64_e32 v[112:113], 0
	v_mov_b64_e32 v[114:115], 0
	v_mov_b64_e32 v[116:117], 0
	v_mov_b64_e32 v[118:119], 0
	v_mov_b64_e32 v[120:121], 0
	v_mov_b64_e32 v[122:123], 0
	v_mov_b64_e32 v[124:125], 0
	v_mov_b64_e32 v[126:127], 0
	s_addc_u32 s47, s43, 0
	s_mov_b32 s95, -2

;     __device__ bool next(int i, Unit& u) const { if (!so.next(i, u)) return false; u.ks = u.pn >= 16 ? 1 : 0; return true; }
;     __device__ bool next(int i, Unit& u) const {
;         const long L = (long)i * G + c; if (L >= (long)nm * nn * ns) return false;
;         const int idx = (int)L; u.ks = idx % ns; const int tile = idx / ns; u.pm = pm0 + tile % nm; u.pn = tile / nm; return true;
; template <class Epi, class Order>
; __device__ __forceinline__ void gemm_phase(LAS unsigned char* lds, const Gemm g, const Order& S, const Epi& E) {
;     ...
; #pragma unroll
;         for (int a = 0; a < 2; ++a)
; #pragma unroll
;             for (int b = 0; b < 2; ++b)
; #pragma unroll
;                 for (int m = 0; m < 4; ++m)
; #pragma unroll
;                     for (int n = 0; n < 2; ++n) acc[a][b][m][n] = (f32x4){0.f, 0.f, 0.f, 0.f};
;         cur = nxt; cA = nA; cB = nB; ++ui;
.LBB0_315:
	s_add_u32 s20, s20, 0x160080
	s_addc_u32 s21, s21, 0
	s_add_u32 s17, s22, 0x100
	v_mov_b64_e32 v[0:1], 0
	v_mov_b64_e32 v[2:3], 0
	v_mov_b64_e32 v[4:5], 0
	v_mov_b64_e32 v[6:7], 0
	v_mov_b64_e32 v[8:9], 0
	v_mov_b64_e32 v[10:11], 0
	v_mov_b64_e32 v[12:13], 0
	v_mov_b64_e32 v[14:15], 0
	v_mov_b64_e32 v[16:17], 0
	v_mov_b64_e32 v[18:19], 0
	v_mov_b64_e32 v[20:21], 0
	v_mov_b64_e32 v[22:23], 0
	v_mov_b64_e32 v[24:25], 0
	v_mov_b64_e32 v[26:27], 0
	v_mov_b64_e32 v[28:29], 0
	v_mov_b64_e32 v[30:31], 0
	v_mov_b64_e32 v[32:33], 0
	v_mov_b64_e32 v[34:35], 0
	v_mov_b64_e32 v[36:37], 0
	v_mov_b64_e32 v[38:39], 0
	v_mov_b64_e32 v[40:41], 0
	v_mov_b64_e32 v[42:43], 0
	v_mov_b64_e32 v[44:45], 0
	v_mov_b64_e32 v[46:47], 0
	v_mov_b64_e32 v[48:49], 0
	v_mov_b64_e32 v[50:51], 0
	v_mov_b64_e32 v[52:53], 0
	v_mov_b64_e32 v[54:55], 0
	v_mov_b64_e32 v[56:57], 0
	v_mov_b64_e32 v[58:59], 0
	v_mov_b64_e32 v[60:61], 0
	v_mov_b64_e32 v[62:63], 0
	v_mov_b64_e32 v[64:65], 0
	v_mov_b64_e32 v[66:67], 0
	v_mov_b64_e32 v[68:69], 0
	v_mov_b64_e32 v[70:71], 0
	v_mov_b64_e32 v[72:73], 0
	v_mov_b64_e32 v[74:75], 0
	v_mov_b64_e32 v[76:77], 0
	v_mov_b64_e32 v[78:79], 0
	v_mov_b64_e32 v[80:81], 0
	v_mov_b64_e32 v[82:83], 0
	v_mov_b64_e32 v[84:85], 0
	v_mov_b64_e32 v[86:87], 0
	v_mov_b64_e32 v[88:89], 0
	v_mov_b64_e32 v[90:91], 0
	v_mov_b64_e32 v[92:93], 0
	v_mov_b64_e32 v[94:95], 0
	v_mov_b64_e32 v[96:97], 0
	v_mov_b64_e32 v[98:99], 0
	v_mov_b64_e32 v[100:101], 0
	v_mov_b64_e32 v[102:103], 0
	v_mov_b64_e32 v[104:105], 0
	v_mov_b64_e32 v[106:107], 0
	v_mov_b64_e32 v[108:109], 0
	v_mov_b64_e32 v[110:111], 0
	v_mov_b64_e32 v[112:113], 0
	v_mov_b64_e32 v[114:115], 0
	v_mov_b64_e32 v[116:117], 0
	v_mov_b64_e32 v[118:119], 0
	v_mov_b64_e32 v[120:121], 0
	v_mov_b64_e32 v[122:123], 0
	v_mov_b64_e32 v[124:125], 0
	v_mov_b64_e32 v[126:127], 0
	s_addc_u32 s96, s23, 0
	s_mov_b32 s97, -2

;     __device__ bool next(int i, Unit& u) const { if (!so.next(i, u)) return false; u.ks = u.pn >= 16 ? 1 : 0; return true; }
; template <class Epi, class Order>
; __device__ __forceinline__ void gemm_phase(LAS unsigned char* lds, const Gemm g, const Order& S, const Epi& E) {
;     ...
;         const bool has_next = S.next(ui + 1, nxt);
;         const char* nA = has_next ? (const char*)g.A + (size_t)nxt.pm * tstep + (size_t)nxt.ks * sstep : cA; const char* nB = has_next ? (const char*)g.Bt + (size_t)nxt.pn * tstep + (size_t)nxt.ks * sstep : cB;
;     ...
; #pragma unroll
;         for (int a = 0; a < 2; ++a)
; #pragma unroll
;             for (int b = 0; b < 2; ++b)
; #pragma unroll
;                 for (int m = 0; m < 4; ++m)
; #pragma unroll
;                     for (int n = 0; n < 2; ++n) acc[a][b][m][n] = (f32x4){0.f, 0.f, 0.f, 0.f};
;         cur = nxt; cA = nA; cB = nB; ++ui;
.LBB0_453:
	s_ashr_i32 s17, s16, 31
	s_xor_b64 s[22:23], s[46:47], -1
	s_lshl_b64 s[20:21], s[16:17], 20
	s_add_u32 s20, s64, s20
	s_addc_u32 s21, s65, s21
	s_and_b64 s[24:25], s[46:47], exec
	s_cselect_b32 s17, s21, s43
	s_cselect_b32 s73, s20, s42
	s_ashr_i32 s11, s10, 31
	s_lshl_b64 s[24:25], s[10:11], 20
	s_add_u32 s36, s33, s24
	s_addc_u32 s37, s35, s25
	s_and_b64 s[24:25], s[46:47], exec
	s_cselect_b32 s11, s37, s45
	s_cselect_b32 s84, s36, s44
	s_add_u32 s42, s42, 0x80080
	s_addc_u32 s43, s43, 0
	s_add_u32 s85, s44, 0x100
	v_mov_b64_e32 v[0:1], 0
	v_mov_b64_e32 v[2:3], 0
	v_mov_b64_e32 v[4:5], 0
	v_mov_b64_e32 v[6:7], 0
	v_mov_b64_e32 v[8:9], 0
	v_mov_b64_e32 v[10:11], 0
	v_mov_b64_e32 v[12:13], 0
	v_mov_b64_e32 v[14:15], 0
	v_mov_b64_e32 v[16:17], 0
	v_mov_b64_e32 v[18:19], 0
	v_mov_b64_e32 v[20:21], 0
	v_mov_b64_e32 v[22:23], 0
	v_mov_b64_e32 v[24:25], 0
	v_mov_b64_e32 v[26:27], 0
	v_mov_b64_e32 v[28:29], 0
	v_mov_b64_e32 v[30:31], 0
	v_mov_b64_e32 v[32:33], 0
	v_mov_b64_e32 v[34:35], 0
	v_mov_b64_e32 v[36:37], 0
	v_mov_b64_e32 v[38:39], 0
	v_mov_b64_e32 v[40:41], 0
	v_mov_b64_e32 v[42:43], 0
	v_mov_b64_e32 v[44:45], 0
	v_mov_b64_e32 v[46:47], 0
	v_mov_b64_e32 v[48:49], 0
	v_mov_b64_e32 v[50:51], 0
	v_mov_b64_e32 v[52:53], 0
	v_mov_b64_e32 v[54:55], 0
	v_mov_b64_e32 v[56:57], 0
	v_mov_b64_e32 v[58:59], 0
	v_mov_b64_e32 v[60:61], 0
	v_mov_b64_e32 v[62:63], 0
	v_mov_b64_e32 v[64:65], 0
	v_mov_b64_e32 v[66:67], 0
	v_mov_b64_e32 v[68:69], 0
	v_mov_b64_e32 v[70:71], 0
	v_mov_b64_e32 v[72:73], 0
	v_mov_b64_e32 v[74:75], 0
	v_mov_b64_e32 v[76:77], 0
	v_mov_b64_e32 v[78:79], 0
	v_mov_b64_e32 v[80:81], 0
	v_mov_b64_e32 v[82:83], 0
	v_mov_b64_e32 v[84:85], 0
	v_mov_b64_e32 v[86:87], 0
	v_mov_b64_e32 v[88:89], 0
	v_mov_b64_e32 v[90:91], 0
	v_mov_b64_e32 v[92:93], 0
	v_mov_b64_e32 v[94:95], 0
	v_mov_b64_e32 v[96:97], 0
	v_mov_b64_e32 v[98:99], 0
	v_mov_b64_e32 v[100:101], 0
	v_mov_b64_e32 v[102:103], 0
	v_mov_b64_e32 v[104:105], 0
	v_mov_b64_e32 v[106:107], 0
	v_mov_b64_e32 v[108:109], 0
	v_mov_b64_e32 v[110:111], 0
	v_mov_b64_e32 v[112:113], 0
	v_mov_b64_e32 v[114:115], 0
	v_mov_b64_e32 v[116:117], 0
	v_mov_b64_e32 v[118:119], 0
	v_mov_b64_e32 v[120:121], 0
	v_mov_b64_e32 v[122:123], 0
	v_mov_b64_e32 v[124:125], 0
	v_mov_b64_e32 v[126:127], 0
	s_addc_u32 s94, s45, 0
	s_mov_b32 s95, -2

; template <class Epi, class Order>
; __device__ __forceinline__ void gemm_phase(LAS unsigned char* lds, const Gemm g, const Order& S, const Epi& E) {
;     ...
;         for (int t = 0; t < nt; t += 2) {
;     ...
; #pragma unroll
;         for (int a = 0; a < 2; ++a)
; #pragma unroll
;             for (int b = 0; b < 2; ++b)
; #pragma unroll
;                 for (int m = 0; m < 4; ++m)
; #pragma unroll
;                     for (int n = 0; n < 2; ++n) acc[a][b][m][n] = (f32x4){0.f, 0.f, 0.f, 0.f};
;         cur = nxt; cA = nA; cB = nB; ++ui;
.LBB0_701:
	v_mov_b32_e32 v131, 0
	s_andn2_b64 vcc, exec, s[12:13]
	v_mov_b32_e32 v130, v131
	s_waitcnt vmcnt(0)
	v_mov_b32_e32 v129, v131
	v_mov_b32_e32 v128, v131
	v_mov_b32_e32 v95, v131
	v_mov_b32_e32 v94, v131
	v_mov_b32_e32 v93, v131
	v_mov_b32_e32 v92, v131
	v_mov_b32_e32 v127, v131
	v_mov_b32_e32 v126, v131
	v_mov_b32_e32 v125, v131
	v_mov_b32_e32 v124, v131
	v_mov_b32_e32 v91, v131
	v_mov_b32_e32 v90, v131
	v_mov_b32_e32 v89, v131
	v_mov_b32_e32 v88, v131
	v_mov_b32_e32 v123, v131
	v_mov_b32_e32 v122, v131
	v_mov_b32_e32 v121, v131
	v_mov_b32_e32 v120, v131
	v_mov_b32_e32 v87, v131
	v_mov_b32_e32 v86, v131
	v_mov_b32_e32 v85, v131
	v_mov_b32_e32 v84, v131
	v_mov_b32_e32 v119, v131
	v_mov_b32_e32 v118, v131
	v_mov_b32_e32 v117, v131
	v_mov_b32_e32 v116, v131
	v_mov_b32_e32 v83, v131
	v_mov_b32_e32 v82, v131
	v_mov_b32_e32 v81, v131
	v_mov_b32_e32 v80, v131
	v_mov_b32_e32 v63, v131
	v_mov_b32_e32 v62, v131
	v_mov_b32_e32 v61, v131
	v_mov_b32_e32 v60, v131
	v_mov_b32_e32 v31, v131
	v_mov_b32_e32 v30, v131
	v_mov_b32_e32 v29, v131
	v_mov_b32_e32 v28, v131
	v_mov_b32_e32 v59, v131
	v_mov_b32_e32 v58, v131
	v_mov_b32_e32 v57, v131
	v_mov_b32_e32 v56, v131
	v_mov_b32_e32 v27, v131
	v_mov_b32_e32 v26, v131
	v_mov_b32_e32 v25, v131
	v_mov_b32_e32 v24, v131
	v_mov_b32_e32 v55, v131
	v_mov_b32_e32 v54, v131
	v_mov_b32_e32 v53, v131
	v_mov_b32_e32 v52, v131
	v_mov_b32_e32 v23, v131
	v_mov_b32_e32 v22, v131
	v_mov_b32_e32 v21, v131
	v_mov_b32_e32 v20, v131
	v_mov_b32_e32 v51, v131
	v_mov_b32_e32 v50, v131
	v_mov_b32_e32 v49, v131
	v_mov_b32_e32 v48, v131
	v_mov_b32_e32 v19, v131
	v_mov_b32_e32 v18, v131
	v_mov_b32_e32 v17, v131
	v_mov_b32_e32 v16, v131
	v_mov_b32_e32 v115, v131
	v_mov_b32_e32 v114, v131
	v_mov_b32_e32 v113, v131
	v_mov_b32_e32 v112, v131
	v_mov_b32_e32 v79, v131
	v_mov_b32_e32 v78, v131
	v_mov_b32_e32 v77, v131
	v_mov_b32_e32 v76, v131
	v_mov_b32_e32 v111, v131
	v_mov_b32_e32 v110, v131
	v_mov_b32_e32 v109, v131
	v_mov_b32_e32 v108, v131
	v_mov_b32_e32 v75, v131
	v_mov_b32_e32 v74, v131
	v_mov_b32_e32 v73, v131
	v_mov_b32_e32 v72, v131
	v_mov_b32_e32 v107, v131
	v_mov_b32_e32 v106, v131
	v_mov_b32_e32 v105, v131
	v_mov_b32_e32 v104, v131
	v_mov_b32_e32 v71, v131
	v_mov_b32_e32 v70, v131
	v_mov_b32_e32 v69, v131
	v_mov_b32_e32 v68, v131
	v_mov_b32_e32 v103, v131
	v_mov_b32_e32 v102, v131
	v_mov_b32_e32 v101, v131
	v_mov_b32_e32 v100, v131
	v_mov_b32_e32 v67, v131
	v_mov_b32_e32 v66, v131
	v_mov_b32_e32 v65, v131
	v_mov_b32_e32 v64, v131
	v_mov_b32_e32 v47, v131
	v_mov_b32_e32 v46, v131
	v_mov_b32_e32 v45, v131
	v_mov_b32_e32 v44, v131
	v_mov_b32_e32 v15, v131
	v_mov_b32_e32 v14, v131
	v_mov_b32_e32 v13, v131
	v_mov_b32_e32 v12, v131
	v_mov_b32_e32 v43, v131
	v_mov_b32_e32 v42, v131
	v_mov_b32_e32 v41, v131
	v_mov_b32_e32 v40, v131
	v_mov_b32_e32 v11, v131
	v_mov_b32_e32 v10, v131
	v_mov_b32_e32 v9, v131
	v_mov_b32_e32 v8, v131
	v_mov_b32_e32 v39, v131
	v_mov_b32_e32 v38, v131
	v_mov_b32_e32 v37, v131
	v_mov_b32_e32 v36, v131
	v_mov_b32_e32 v7, v131
	v_mov_b32_e32 v6, v131
	v_mov_b32_e32 v5, v131
	v_mov_b32_e32 v4, v131
	v_mov_b32_e32 v35, v131
	v_mov_b32_e32 v34, v131
	v_mov_b32_e32 v33, v131
	v_mov_b32_e32 v32, v131
	v_mov_b32_e32 v3, v131
	v_mov_b32_e32 v2, v131
	v_mov_b32_e32 v1, v131
	v_mov_b32_e32 v0, v131
	s_cbranch_vccnz .LBB0_694
	s_add_u32 s0, s36, 0x10080
	s_addc_u32 s1, s37, 0
	s_add_u32 s15, s22, 0x100
	v_mov_b64_e32 v[0:1], 0
	v_mov_b64_e32 v[2:3], 0
	v_mov_b64_e32 v[4:5], 0
	v_mov_b64_e32 v[6:7], 0
	v_mov_b64_e32 v[8:9], 0
	v_mov_b64_e32 v[10:11], 0
	v_mov_b64_e32 v[12:13], 0
	v_mov_b64_e32 v[14:15], 0
	v_mov_b64_e32 v[16:17], 0
	v_mov_b64_e32 v[18:19], 0
	v_mov_b64_e32 v[20:21], 0
	v_mov_b64_e32 v[22:23], 0
	v_mov_b64_e32 v[24:25], 0
	v_mov_b64_e32 v[26:27], 0
	v_mov_b64_e32 v[28:29], 0
	v_mov_b64_e32 v[30:31], 0
	v_mov_b64_e32 v[32:33], 0
	v_mov_b64_e32 v[34:35], 0
	v_mov_b64_e32 v[36:37], 0
	v_mov_b64_e32 v[38:39], 0
	v_mov_b64_e32 v[40:41], 0
	v_mov_b64_e32 v[42:43], 0
	v_mov_b64_e32 v[44:45], 0
	v_mov_b64_e32 v[46:47], 0
	v_mov_b64_e32 v[48:49], 0
	v_mov_b64_e32 v[50:51], 0
	v_mov_b64_e32 v[52:53], 0
	v_mov_b64_e32 v[54:55], 0
	v_mov_b64_e32 v[56:57], 0
	v_mov_b64_e32 v[58:59], 0
	v_mov_b64_e32 v[60:61], 0
	v_mov_b64_e32 v[62:63], 0
	v_mov_b64_e32 v[64:65], 0
	v_mov_b64_e32 v[66:67], 0
	v_mov_b64_e32 v[68:69], 0
	v_mov_b64_e32 v[70:71], 0
	v_mov_b64_e32 v[72:73], 0
	v_mov_b64_e32 v[74:75], 0
	v_mov_b64_e32 v[76:77], 0
	v_mov_b64_e32 v[78:79], 0
	v_mov_b64_e32 v[80:81], 0
	v_mov_b64_e32 v[82:83], 0
	v_mov_b64_e32 v[84:85], 0
	v_mov_b64_e32 v[86:87], 0
	v_mov_b64_e32 v[88:89], 0
	v_mov_b64_e32 v[90:91], 0
	v_mov_b64_e32 v[92:93], 0
	v_mov_b64_e32 v[94:95], 0
	v_mov_b64_e32 v[100:101], 0
	v_mov_b64_e32 v[102:103], 0
	v_mov_b64_e32 v[104:105], 0
	v_mov_b64_e32 v[106:107], 0
	v_mov_b64_e32 v[108:109], 0
	v_mov_b64_e32 v[110:111], 0
	v_mov_b64_e32 v[112:113], 0
	v_mov_b64_e32 v[114:115], 0
	v_mov_b64_e32 v[116:117], 0
	v_mov_b64_e32 v[118:119], 0
	v_mov_b64_e32 v[120:121], 0
	v_mov_b64_e32 v[122:123], 0
	v_mov_b64_e32 v[124:125], 0
	v_mov_b64_e32 v[126:127], 0
	v_mov_b64_e32 v[128:129], 0
	v_mov_b64_e32 v[130:131], 0
	s_addc_u32 s17, s23, 0
	s_mov_b32 s22, 0

;     __device__ bool next(int i, Unit& u) const { if (!so.next(i, u)) return false; u.ks = u.pn >= 16 ? 1 : 0; return true; }
; template <class Epi, class Order>
; __device__ __forceinline__ void gemm_phase(LAS unsigned char* lds, const Gemm g, const Order& S, const Epi& E) {
;     ...
;         const bool has_next = S.next(ui + 1, nxt);
;         const char* nA = has_next ? (const char*)g.A + (size_t)nxt.pm * tstep + (size_t)nxt.ks * sstep : cA; const char* nB = has_next ? (const char*)g.Bt + (size_t)nxt.pn * tstep + (size_t)nxt.ks * sstep : cB;
;     ...
; #pragma unroll
;         for (int a = 0; a < 2; ++a)
; #pragma unroll
;             for (int b = 0; b < 2; ++b)
; #pragma unroll
;                 for (int m = 0; m < 4; ++m)
; #pragma unroll
;                     for (int n = 0; n < 2; ++n) acc[a][b][m][n] = (f32x4){0.f, 0.f, 0.f, 0.f};
;         cur = nxt; cA = nA; cB = nB; ++ui;
.LBB0_1140:
	s_ashr_i32 s11, s10, 31
	v_cmp_lt_i64_e32 vcc, s[12:13], v[140:141]
	s_lshl_b64 s[12:13], s[10:11], 20
	s_add_u32 s12, s64, s12
	s_addc_u32 s13, s65, s13
	s_and_b64 s[14:15], vcc, exec
	s_cselect_b32 s11, s13, s19
	s_cselect_b32 s57, s12, s18
	s_ashr_i32 s9, s8, 31
	s_lshl_b64 s[14:15], s[8:9], 20
	s_add_u32 s14, s33, s14
	s_addc_u32 s15, s35, s15
	s_and_b64 s[22:23], vcc, exec
	s_cselect_b32 s9, s15, s21
	s_cselect_b32 s58, s14, s20
	s_add_u32 s18, s18, 0x80080
	s_addc_u32 s19, s19, 0
	s_add_u32 s59, s20, 0x100
	v_mov_b64_e32 v[0:1], 0
	v_mov_b64_e32 v[2:3], 0
	v_mov_b64_e32 v[4:5], 0
	v_mov_b64_e32 v[6:7], 0
	v_mov_b64_e32 v[8:9], 0
	v_mov_b64_e32 v[10:11], 0
	v_mov_b64_e32 v[12:13], 0
	v_mov_b64_e32 v[14:15], 0
	v_mov_b64_e32 v[16:17], 0
	v_mov_b64_e32 v[18:19], 0
	v_mov_b64_e32 v[20:21], 0
	v_mov_b64_e32 v[22:23], 0
	v_mov_b64_e32 v[24:25], 0
	v_mov_b64_e32 v[26:27], 0
	v_mov_b64_e32 v[28:29], 0
	v_mov_b64_e32 v[30:31], 0
	v_mov_b64_e32 v[32:33], 0
	v_mov_b64_e32 v[34:35], 0
	v_mov_b64_e32 v[36:37], 0
	v_mov_b64_e32 v[38:39], 0
	v_mov_b64_e32 v[40:41], 0
	v_mov_b64_e32 v[42:43], 0
	v_mov_b64_e32 v[44:45], 0
	v_mov_b64_e32 v[46:47], 0
	v_mov_b64_e32 v[48:49], 0
	v_mov_b64_e32 v[50:51], 0
	v_mov_b64_e32 v[52:53], 0
	v_mov_b64_e32 v[54:55], 0
	v_mov_b64_e32 v[56:57], 0
	v_mov_b64_e32 v[58:59], 0
	v_mov_b64_e32 v[60:61], 0
	v_mov_b64_e32 v[62:63], 0
	v_mov_b64_e32 v[64:65], 0
	v_mov_b64_e32 v[66:67], 0
	v_mov_b64_e32 v[68:69], 0
	v_mov_b64_e32 v[70:71], 0
	v_mov_b64_e32 v[72:73], 0
	v_mov_b64_e32 v[74:75], 0
	v_mov_b64_e32 v[76:77], 0
	v_mov_b64_e32 v[78:79], 0
	v_mov_b64_e32 v[80:81], 0
	v_mov_b64_e32 v[82:83], 0
	v_mov_b64_e32 v[84:85], 0
	v_mov_b64_e32 v[86:87], 0
	v_mov_b64_e32 v[88:89], 0
	v_mov_b64_e32 v[90:91], 0
	v_mov_b64_e32 v[92:93], 0
	v_mov_b64_e32 v[94:95], 0
	v_mov_b64_e32 v[96:97], 0
	v_mov_b64_e32 v[98:99], 0
	v_mov_b64_e32 v[100:101], 0
	v_mov_b64_e32 v[102:103], 0
	v_mov_b64_e32 v[104:105], 0
	v_mov_b64_e32 v[106:107], 0
	v_mov_b64_e32 v[108:109], 0
	v_mov_b64_e32 v[110:111], 0
	v_mov_b64_e32 v[112:113], 0
	v_mov_b64_e32 v[114:115], 0
	v_mov_b64_e32 v[116:117], 0
	v_mov_b64_e32 v[118:119], 0
	v_mov_b64_e32 v[120:121], 0
	v_mov_b64_e32 v[122:123], 0
	v_mov_b64_e32 v[124:125], 0
	v_mov_b64_e32 v[126:127], 0
	s_addc_u32 s60, s21, 0
	s_mov_b32 s61, -2
